# RWKV carry step: the 16 serialized LDS partial reads (each behind lgkmcnt(0)) batched 8 deep through spare registers; on top of attention/scan/cprep/epilogue edits
# speedup vs baseline: 1.0079x; 1.0020x over previous
; __device__ __forceinline__ void carry_item(Frame& F, const Args& a, int l, int bh, unsigned char* ws) {
;     ...
;         if (kh == 0) {
;             float* so = SS + (size_t)(c + 1) * 4096;
; #pragma unroll
;             for (int r = 0; r < 16; ++r) { const int jo = ((r & 3) + 8 * (r >> 2)) * 64;
;                 const float nv = (acc0[r] + acc1[r]) + Pp[(bj * 2 + bi) * 1024 + r * 64 + lane] + lt[r];
;                 St[lo_o + jo] = nv;
;                 if (c < 63) so[lo_o + jo] = nv;
;                 else { const int j = 32 * bi + (r & 3) + 8 * (r >> 2) + 4 * hi, v = 32 * bj + l31; ((float*)a.out)[O_WP + ((size_t)(l * 16 + bh)) * 4096 + v * 64 + j] = nv; } }
.LBB0_998:
	s_waitcnt lgkmcnt(0)
	s_barrier
	s_and_b64 vcc, exec, s[0:1]
	s_cbranch_vccnz .LBB0_1000
	v_add_u32_e32 v12, s4, v37
	ds_read_b32 v184, v12 offset:16384
	ds_read_b32 v185, v12 offset:16640
	ds_read_b32 v186, v12 offset:16896
	ds_read_b32 v187, v12 offset:17152
	ds_read_b32 v188, v12 offset:17408
	ds_read_b32 v189, v12 offset:17664
	ds_read_b32 v190, v12 offset:17920
	ds_read_b32 v191, v12 offset:18176
	s_waitcnt lgkmcnt(7)
	v_add_f32_e32 v10, v130, v184
	v_add_f32_e32 v13, v129, v10
	v_add_co_u32_e32 v10, vcc, 0x45b04000, v76
	ds_write_b32 v78, v13
	s_nop 0
	v_addc_co_u32_e32 v11, vcc, 0, v77, vcc
	global_store_dword v[10:11], v13, off
	s_waitcnt lgkmcnt(7)
	v_add_f32_e32 v10, v128, v185
	v_add_f32_e32 v13, v121, v10
	ds_write_b32 v78, v13 offset:256
	v_lshl_add_u64 v[10:11], v[44:45], 0, s[2:3]
	global_store_dword v[10:11], v13, off
	s_waitcnt lgkmcnt(7)
	v_add_f32_e32 v10, v127, v186
	v_add_f32_e32 v13, v125, v10
	ds_write_b32 v78, v13 offset:512
	v_lshl_add_u64 v[10:11], v[46:47], 0, s[2:3]
	global_store_dword v[10:11], v13, off
	s_waitcnt lgkmcnt(7)
	v_add_f32_e32 v10, v126, v187
	v_add_f32_e32 v13, v122, v10
	ds_write_b32 v78, v13 offset:768
	v_lshl_add_u64 v[10:11], v[48:49], 0, s[2:3]
	global_store_dword v[10:11], v13, off
	s_waitcnt lgkmcnt(7)
	v_add_f32_e32 v10, v21, v188
	v_add_f32_e32 v13, v124, v10
	ds_write_b32 v78, v13 offset:2048
	v_lshl_add_u64 v[10:11], v[50:51], 0, s[2:3]
	global_store_dword v[10:11], v13, off
	s_waitcnt lgkmcnt(7)
	v_add_f32_e32 v10, v20, v189
	v_add_f32_e32 v13, v120, v10
	ds_write_b32 v78, v13 offset:2304
	v_lshl_add_u64 v[10:11], v[52:53], 0, s[2:3]
	global_store_dword v[10:11], v13, off
	s_waitcnt lgkmcnt(7)
	v_add_f32_e32 v10, v19, v190
	v_add_f32_e32 v13, v123, v10
	ds_write_b32 v78, v13 offset:2560
	v_lshl_add_u64 v[10:11], v[54:55], 0, s[2:3]
	global_store_dword v[10:11], v13, off
	s_waitcnt lgkmcnt(7)
	v_add_f32_e32 v10, v18, v191
	v_add_f32_e32 v13, v119, v10
	ds_write_b32 v78, v13 offset:2816
	v_lshl_add_u64 v[10:11], v[56:57], 0, s[2:3]
	global_store_dword v[10:11], v13, off
	ds_read_b32 v184, v12 offset:18432
	ds_read_b32 v185, v12 offset:18688
	ds_read_b32 v186, v12 offset:18944
	ds_read_b32 v187, v12 offset:19200
	ds_read_b32 v188, v12 offset:19456
	ds_read_b32 v189, v12 offset:19712
	ds_read_b32 v190, v12 offset:19968
	ds_read_b32 v191, v12 offset:20224
	s_waitcnt lgkmcnt(7)
	v_add_f32_e32 v9, v9, v184
	v_add_f32_e32 v9, v118, v9
	ds_write_b32 v78, v9 offset:4096
	v_lshl_add_u64 v[10:11], v[58:59], 0, s[2:3]
	global_store_dword v[10:11], v9, off
	s_waitcnt lgkmcnt(7)
	v_add_f32_e32 v8, v8, v185
	v_add_f32_e32 v10, v99, v8
	ds_write_b32 v78, v10 offset:4352
	v_lshl_add_u64 v[8:9], v[60:61], 0, s[2:3]
	global_store_dword v[8:9], v10, off
	s_waitcnt lgkmcnt(7)
	v_add_f32_e32 v7, v7, v186
	v_add_f32_e32 v7, v117, v7
	ds_write_b32 v78, v7 offset:4608
	v_lshl_add_u64 v[8:9], v[62:63], 0, s[2:3]
	global_store_dword v[8:9], v7, off
	s_waitcnt lgkmcnt(7)
	v_add_f32_e32 v6, v6, v187
	v_add_f32_e32 v8, v97, v6
	ds_write_b32 v78, v8 offset:4864
	v_lshl_add_u64 v[6:7], v[64:65], 0, s[2:3]
	global_store_dword v[6:7], v8, off
	s_waitcnt lgkmcnt(7)
	v_add_f32_e32 v5, v5, v188
	v_add_f32_e32 v5, v105, v5
	ds_write_b32 v78, v5 offset:6144
	v_lshl_add_u64 v[6:7], v[66:67], 0, s[2:3]
	global_store_dword v[6:7], v5, off
	s_waitcnt lgkmcnt(7)
	v_add_f32_e32 v4, v4, v189
	v_add_f32_e32 v6, v96, v4
	ds_write_b32 v78, v6 offset:6400
	v_lshl_add_u64 v[4:5], v[68:69], 0, s[2:3]
	global_store_dword v[4:5], v6, off
	s_waitcnt lgkmcnt(7)
	v_add_f32_e32 v3, v3, v190
	v_add_f32_e32 v3, v98, v3
	ds_write_b32 v78, v3 offset:6656
	v_lshl_add_u64 v[4:5], v[70:71], 0, s[2:3]
	global_store_dword v[4:5], v3, off
	s_waitcnt lgkmcnt(7)
	v_add_f32_e32 v2, v2, v191
	v_add_f32_e32 v4, v95, v2
	v_lshl_add_u64 v[2:3], v[72:73], 0, s[2:3]
	ds_write_b32 v78, v4 offset:6912
	global_store_dword v[2:3], v4, off
